# grid barrier: leader invalidate issued with the write-back, leader post-release waits dropped
# baseline (speedup 1.0000x reference)
.LBB0_111:
	s_andn2_saveexec_b64 s[2:3], s[6:7]
	s_cbranch_execz .LBB0_131
	s_mov_b64 s[6:7], exec
	buffer_wbl2 sc1
	buffer_inv sc1
	s_waitcnt lgkmcnt(0)
	s_waitcnt vmcnt(0)
	v_mbcnt_lo_u32_b32 v2, s6, 0
	v_mbcnt_hi_u32_b32 v2, s7, v2
	v_cmp_eq_u32_e32 vcc, 0, v2
	s_and_saveexec_b64 s[8:9], vcc
	s_cbranch_execz .LBB0_114
	s_bcnt1_i32_b64 s2, s[6:7]
	v_mov_b32_e32 v3, 0x3000
	v_mov_b32_e32 v4, s2
	global_atomic_add v3, v3, v4, s[64:65] offset:1024 sc0

.LBB0_128:
	s_or_b64 exec, exec, s[6:7]
	s_mov_b64 s[6:7], exec
	v_mbcnt_lo_u32_b32 v1, s6, 0
	v_mbcnt_hi_u32_b32 v1, s7, v1
	v_cmp_eq_u32_e32 vcc, 0, v1
	s_and_saveexec_b64 s[8:9], vcc
	s_cbranch_execz .LBB0_130
	s_bcnt1_i32_b64 s2, s[6:7]
	v_mov_b32_e32 v1, 0x2000
	v_mov_b32_e32 v2, s2
.LBB0_130:
	s_or_b64 exec, exec, s[8:9]
.LBB0_131:
	s_or_b64 exec, exec, s[0:1]
	s_mov_b64 s[0:1], 0x8000
	v_lshl_add_u64 v[162:163], v[154:155], 0, s[0:1]
	s_mov_b64 s[0:1], 0x78000
	s_lshl_b32 s70, s83, 9
	v_lshl_add_u64 v[164:165], v[154:155], 0, s[0:1]
	v_or_b32_e32 v2, s70, v0
	s_mov_b32 s0, 0xd800
	v_cmp_gt_i32_e32 vcc, s0, v2
	s_waitcnt lgkmcnt(0)
	s_barrier
	s_and_saveexec_b64 s[0:1], vcc
	s_cbranch_execz .LBB0_134
	v_readlane_b32 s2, v254, 0
	v_readlane_b32 s3, v254, 1
	s_load_dword s8, s[2:3], 0xf8
	s_load_dwordx2 s[4:5], s[2:3], 0x58
	s_mov_b64 s[6:7], 0
	s_mov_b32 s2, 0x2aaaaaab
	s_mov_b32 s3, 0x6c000
	s_waitcnt lgkmcnt(0)
	s_lshl_b32 s8, s8, 9
	s_mov_b32 s9, 0xd8000
	s_mov_b32 s10, 0x144000
	s_mov_b32 s11, 0x1b0000
	s_mov_b32 s12, 0x21c000
	s_mov_b32 s13, 0x288000
	s_mov_b32 s14, 0xd7ff

.LBB0_230:
	s_or_b64 exec, exec, s[8:9]
.LBB0_231:
	v_writelane_b32 v254, s64, 5
	s_nop 1
	v_writelane_b32 v254, s65, 6
	s_or_b64 exec, exec, s[0:1]
	v_readlane_b32 s2, v254, 0
	v_readlane_b32 s3, v254, 1
	s_waitcnt lgkmcnt(0)
	s_barrier
	s_mov_b64 s[0:1], 0x4280000
	s_load_dword s84, s[2:3], 0xf8
	s_load_dwordx4 s[12:15], s[2:3], 0xe8
	v_lshl_add_u64 v[156:157], v[154:155], 0, s[0:1]
	s_mov_b64 s[0:1], 0x400000
	v_lshl_add_u64 v[130:131], v[154:155], 0, s[0:1]
	s_add_u32 s0, s2, 0xf8
	s_addc_u32 s1, s3, 0
	v_writelane_b32 v254, s0, 7
	s_waitcnt lgkmcnt(0)
	s_ashr_i32 s85, s84, 31
	v_lshlrev_b32_e32 v1, 6, v0
	v_writelane_b32 v254, s1, 8
	s_ashr_i32 s0, s83, 31
	v_writelane_b32 v254, s0, 9
	s_add_u32 s0, s14, 0x4000
	s_addc_u32 s1, s15, 0
	s_add_u32 s16, s12, 0x5000000
	s_addc_u32 s17, s13, 0
	s_add_u32 s18, s14, 0x6000
	s_addc_u32 s19, s15, 0
	s_add_u32 s22, s14, 0xea80000
	s_addc_u32 s23, s15, 0
	s_add_u32 s2, s14, 0xe680000
	s_addc_u32 s3, s15, 0
	s_add_u32 s24, s12, 0x5400000
	v_and_b32_e32 v166, 64, v1
	s_addc_u32 s25, s13, 0
	s_mov_b64 s[4:5], 0x42c0080
	v_mov_b32_e32 v133, 0
	v_lshlrev_b32_e32 v132, 1, v166
	s_add_u32 s33, s14, 0x9280000
	v_lshl_add_u64 v[160:161], v[154:155], 0, s[4:5]
	s_mov_b64 s[4:5], 0x400100
	v_writelane_b32 v254, s83, 10
	v_lshrrev_b32_e32 v226, 1, v0
	v_lshl_add_u64 v[158:159], v[156:157], 0, v[132:133]
	v_lshl_add_u64 v[134:135], v[130:131], 0, v[132:133]
	s_addc_u32 s71, s15, 0
	v_lshl_add_u64 v[136:137], v[154:155], 0, s[4:5]
	s_mov_b32 s27, 0
	v_mov_b64_e32 v[138:139], 0x3c0
	v_mov_b64_e32 v[140:141], 0x3bf
	s_movk_i32 s72, 0x79
	s_mov_b64 s[28:29], 0x40000
	s_mov_b64 s[30:31], 0x80
	s_mov_b32 s73, 0x8000
	s_mov_b64 s[34:35], 0x40080
	s_movk_i32 s74, 0x108
	s_mov_b32 s75, 0x7280000
	s_movk_i32 s76, 0xa0
	s_mov_b32 s77, 0x400000
	s_movk_i32 s78, 0x210
	v_mov_b32_e32 v1, 0x358637bd
	s_mov_b32 s79, 0x800000
	s_mov_b32 s80, 0xd280000
	s_movk_i32 s81, 0x1080
	v_mov_b32_e32 v167, 1
	v_mbcnt_hi_u32_b32 v209, -1, v21
	s_mov_b32 s82, 0
	v_writelane_b32 v254, s84, 11
	v_writelane_b32 v254, s85, 12
	s_branch .LBB0_234

.LBB0_447:
	s_andn2_saveexec_b64 s[2:3], s[6:7]
	s_cbranch_execz .LBB0_467
	s_mov_b64 s[6:7], exec
	buffer_wbl2 sc1
	buffer_inv sc1
	s_waitcnt lgkmcnt(0)
	s_waitcnt vmcnt(0)
	v_mbcnt_lo_u32_b32 v2, s6, 0
	v_mbcnt_hi_u32_b32 v2, s7, v2
	v_cmp_eq_u32_e32 vcc, 0, v2
	s_and_saveexec_b64 s[8:9], vcc
	s_cbranch_execz .LBB0_450
	s_bcnt1_i32_b64 s2, s[6:7]
	v_mov_b32_e32 v3, 0x3000
	v_mov_b32_e32 v4, s2
	global_atomic_add v3, v3, v4, s[80:81] offset:1024 sc0

.LBB0_466:
	s_or_b64 exec, exec, s[8:9]
.LBB0_467:
	s_or_b64 exec, exec, s[0:1]
	v_readlane_b32 s0, v254, 0
	v_readlane_b32 s1, v254, 1
	s_waitcnt lgkmcnt(0)
	s_barrier
	s_load_dwordx2 s[4:5], s[0:1], 0xf0
	v_cndmask_b32_e64 v1, 0, 1, s[20:21]
	v_cmp_ne_u32_e64 s[0:1], 1, v1
	s_andn2_b64 vcc, exec, s[20:21]
	s_nop 0
	v_writelane_b32 v254, s0, 13
	s_nop 1
	v_writelane_b32 v254, s1, 14
	s_cbranch_vccnz .LBB0_679
	s_waitcnt lgkmcnt(0)
	s_add_u32 s44, s4, 0x4280000
	s_addc_u32 s45, s5, 0
	s_add_u32 s46, s4, 0x6000
	s_addc_u32 s47, s5, 0
	s_add_u32 s68, s4, 0x7280000
	s_addc_u32 s69, s5, 0
	s_add_u32 s71, s4, 0x8280000
	s_addc_u32 s72, s5, 0
	s_add_u32 s73, s4, 0x9280000
	s_addc_u32 s74, s5, 0
	s_add_u32 s75, s4, 0xa280000
	s_addc_u32 s76, s5, 0
	v_readlane_b32 s0, v254, 0
	s_add_u32 s77, s4, 0x4080000
	v_readlane_b32 s1, v254, 1
	s_addc_u32 s78, s5, 0
	s_load_dwordx2 s[50:51], s[0:1], 0x98
	s_add_u32 s79, s4, 0x4180000
	s_addc_u32 s80, s5, 0
	s_add_u32 s48, s4, 0xb280000
	s_addc_u32 s49, s5, 0
	s_mov_b32 s53, 0
	v_mov_b32_e32 v93, 0
	s_mov_b64 s[54:55], 0x2000
	v_mov_b32_e32 v167, 0x3f80
	v_mov_b32_e32 v227, 0x3727c5ac
	s_mov_b32 s81, 0x800000
	s_movk_i32 s82, 0xc00
	s_branch .LBB0_470

.LBB0_735:
	s_or_b64 exec, exec, s[8:9]
.LBB0_736:
	s_or_b64 exec, exec, s[0:1]
	s_mov_b64 s[0:1], 0xb80000
	v_lshl_add_u64 v[132:133], v[154:155], 0, s[0:1]
	v_readlane_b32 s0, v254, 0
	v_readlane_b32 s1, v254, 1
	s_waitcnt lgkmcnt(0)
	s_barrier
	s_load_dwordx4 s[8:11], s[0:1], 0x0
	v_mov_b32_e32 v135, 0
	s_load_dwordx2 s[0:1], s[0:1], 0xf0
	v_lshlrev_b32_e32 v130, 1, v166
	v_mov_b32_e32 v131, v135
	s_waitcnt lgkmcnt(0)
	s_cmp_lg_u64 s[8:9], 0
	s_cselect_b64 s[4:5], -1, 0
	s_add_u32 s12, s0, 0xd580000
	v_lshl_add_u64 v[136:137], v[132:133], 0, v[130:131]
	s_addc_u32 s13, s1, 0
	s_mov_b32 s2, 0
	v_mov_b64_e32 v[138:139], 0x100
	v_mov_b64_e32 v[140:141], 0xff
	s_movk_i32 s3, 0x600
	s_movk_i32 s24, 0x2000
	s_mov_b64 s[14:15], 0x60000
	s_movk_i32 s25, 0x6000
	s_mov_b64 s[16:17], 0x80
	s_mov_b64 s[18:19], 0x60080
	s_movk_i32 s26, 0xc00
	s_movk_i32 s27, 0x108
	s_mov_b64 s[20:21], 0xa000
	s_movk_i32 s28, 0x210
	v_mov_b32_e32 v1, 1
	v_mov_b32_e32 v131, 0xc0000
	s_branch .LBB0_739

.LBB0_831:
	s_or_b64 exec, exec, s[8:9]
.LBB0_832:
	s_or_b64 exec, exec, s[0:1]
	v_readlane_b32 s0, v254, 13
	v_readlane_b32 s1, v254, 14
	v_mov_b32_e32 v18, v0
	s_and_b64 vcc, exec, s[0:1]
	s_waitcnt lgkmcnt(0)
	s_barrier
	s_cbranch_vccnz .LBB0_850
	v_and_b32_e32 v2, 64, v209
	v_add_u32_e32 v2, 64, v2
	v_xor_b32_e32 v4, 1, v209
	v_cmp_lt_i32_e32 vcc, v4, v2
	v_readlane_b32 s2, v254, 0
	v_readlane_b32 s3, v254, 1
	v_cndmask_b32_e32 v4, v209, v4, vcc
	v_lshlrev_b32_e32 v50, 2, v4
	v_xor_b32_e32 v4, 2, v209
	v_cmp_lt_i32_e32 vcc, v4, v2
	s_load_dwordx2 s[0:1], s[2:3], 0x68
	s_load_dwordx2 s[4:5], s[2:3], 0xf0
	v_cndmask_b32_e32 v4, v209, v4, vcc
	v_lshlrev_b32_e32 v51, 2, v4
	v_xor_b32_e32 v4, 4, v209
	v_cmp_lt_i32_e32 vcc, v4, v2
	v_lshlrev_b32_e32 v48, 2, v18
	v_and_b32_e32 v3, 0xfc, v48
	v_cndmask_b32_e32 v4, v209, v4, vcc
	v_lshlrev_b32_e32 v52, 2, v4
	v_xor_b32_e32 v4, 8, v209
	v_cmp_lt_i32_e32 vcc, v4, v2
	s_movk_i32 s2, 0x400
	v_lshl_add_u32 v49, v3, 2, 0
	v_cndmask_b32_e32 v4, v209, v4, vcc
	v_lshlrev_b32_e32 v53, 2, v4
	v_xor_b32_e32 v4, 16, v209
	v_cmp_lt_i32_e32 vcc, v4, v2
	v_cmp_gt_i32_e64 s[6:7], s2, v18
	s_mov_b64 s[2:3], 0xd580000
	v_cndmask_b32_e32 v4, v209, v4, vcc
	v_lshlrev_b32_e32 v54, 2, v4
	v_xor_b32_e32 v4, 32, v209
	v_cmp_lt_i32_e32 vcc, v4, v2
	s_movk_i32 s28, 0x1ff
	v_ashrrev_i32_e32 v1, 4, v18
	v_cndmask_b32_e32 v2, v209, v4, vcc
	v_max_i32_e32 v4, 0x200, v18
	v_sub_u32_e32 v4, v4, v18
	v_add_u32_e32 v4, 0x1ff, v4
	v_lshlrev_b32_e32 v55, 2, v2
	v_lshlrev_b32_e32 v2, 1, v3
	v_mov_b32_e32 v3, 0
	v_lshrrev_b32_e32 v5, 9, v4
	s_waitcnt lgkmcnt(0)
	v_lshl_add_u64 v[2:3], s[4:5], 0, v[2:3]
	v_add_u32_e32 v6, 1, v5
	v_add_u32_e32 v5, -1, v5
	v_lshl_add_u64 v[20:21], v[2:3], 0, s[2:3]
	s_add_u32 s2, s4, 0x8000
	v_lshrrev_b32_e32 v7, 1, v5
	s_addc_u32 s3, s5, 0
	v_add_u32_e32 v7, 1, v7
	v_cmp_lt_u32_e64 s[8:9], s28, v4
	v_and_b32_e32 v4, 0xfffffe, v6
	v_and_b32_e32 v57, 3, v7
	s_mov_b64 s[16:17], 0x4280000
	s_add_u32 s29, s4, 0xb000
	v_and_b32_e32 v1, -4, v1
	v_lshl_add_u32 v56, v4, 9, v18
	v_add_u32_e32 v19, 0x200, v18
	v_cmp_lt_u32_e64 s[10:11], 5, v5
	v_and_b32_e32 v58, -4, v7
	v_cmp_ne_u32_e64 s[12:13], 0, v57
	v_cmp_ne_u32_e64 s[14:15], v6, v4
	s_waitcnt vmcnt(4)
	v_lshl_add_u64 v[22:23], v[2:3], 0, s[16:17]
	v_add_u32_e32 v59, 0, v48
	s_addc_u32 s30, s5, 0
	s_movk_i32 s31, 0x3000
	s_movk_i32 s33, 0x4000
	s_mov_b64 s[4:5], 0x800
	v_mov_b32_e32 v60, 0x358637bd
	s_mov_b32 s34, 0x800000
	s_mov_b32 s35, s83
	s_branch .LBB0_835

.LBB0_901:
	s_or_b64 exec, exec, s[8:9]
.LBB0_902:
	s_or_b64 exec, exec, s[0:1]
	v_readlane_b32 s2, v254, 0
	v_readlane_b32 s3, v254, 1
	s_waitcnt lgkmcnt(0)
	s_barrier
	s_load_dwordx4 s[12:15], s[2:3], 0xd0
	s_nop 0
	s_load_dwordx2 s[2:3], s[2:3], 0xf0
	s_mov_b64 s[0:1], 0x1680000
	v_lshl_add_u64 v[132:133], v[154:155], 0, s[0:1]
	v_mov_b32_e32 v135, 0
	v_mov_b32_e32 v131, v135
	s_waitcnt lgkmcnt(0)
	s_add_u32 s0, s2, 0x7280000
	s_addc_u32 s1, s3, 0
	s_add_u32 s2, s2, 0xca80000
	s_mov_b64 s[4:5], 0x1680100
	v_lshl_add_u64 v[136:137], v[132:133], 0, v[130:131]
	s_addc_u32 s3, s3, 0
	v_lshl_add_u64 v[138:139], v[154:155], 0, s[4:5]
	s_mov_b32 s4, 0
	v_mov_b64_e32 v[140:141], 0x580
	v_mov_b64_e32 v[142:143], 0x57f
	s_movk_i32 s33, 0xb1
	s_movk_i32 s44, 0x2000
	s_movk_i32 s45, 0x400
	s_mov_b64 s[10:11], 0x40000
	s_mov_b64 s[16:17], 0x80
	s_mov_b64 s[18:19], 0x40080
	s_mov_b64 s[20:21], 0x4280100
	s_movk_i32 s46, 0xff
	s_movk_i32 s47, 0x108
	s_mov_b64 s[22:23], 0x5800
	s_movk_i32 s48, 0x5000
	s_mov_b64 s[24:25], 0xb000
	s_mov_b64 s[26:27], 0x2c00
	s_mov_b64 s[28:29], 0x8400
	s_mov_b64 s[30:31], 0xdc00
	s_movk_i32 s49, 0xfdf0
	s_movk_i32 s50, 0x1600
	s_movk_i32 s51, 0x210
	s_movk_i32 s52, 0x1ff
	s_movk_i32 s53, 0x5800
	v_mov_b32_e32 v131, 1
	s_mov_b32 s54, 0
	s_branch .LBB0_905

.LBB0_1092:
	s_or_b64 exec, exec, s[8:9]
.LBB0_1093:
	s_or_b64 exec, exec, s[0:1]
	s_waitcnt lgkmcnt(0)
	v_add_u32_e32 v1, s70, v0
	v_add_u32_e32 v2, 0xd800, v1
	s_mov_b32 s0, 0x1b000
	v_cmp_gt_i32_e32 vcc, s0, v2
	s_barrier
	s_and_saveexec_b64 s[0:1], vcc
	s_cbranch_execz .LBB0_1096
	v_readlane_b32 s2, v254, 0
	v_readlane_b32 s3, v254, 1
	s_load_dwordx2 s[4:5], s[2:3], 0x58
	s_lshl_b32 s2, s84, 9
	s_mov_b64 s[6:7], 0
	s_mov_b32 s3, 0x2aaaaaab
	s_mov_b32 s8, 0x1afff

.LBB0_1188:
	s_or_b64 exec, exec, s[8:9]
.LBB0_1189:
	s_or_b64 exec, exec, s[0:1]
	v_readlane_b32 s0, v254, 13
	v_readlane_b32 s1, v254, 14
	v_mov_b32_e32 v18, v0
	s_and_b64 vcc, exec, s[0:1]
	s_waitcnt lgkmcnt(0)
	s_barrier
	s_cbranch_vccnz .LBB0_1207
	v_and_b32_e32 v2, 64, v209
	v_add_u32_e32 v2, 64, v2
	v_xor_b32_e32 v4, 1, v209
	v_cmp_lt_i32_e32 vcc, v4, v2
	v_readlane_b32 s2, v254, 0
	v_readlane_b32 s3, v254, 1
	v_cndmask_b32_e32 v4, v209, v4, vcc
	v_lshlrev_b32_e32 v50, 2, v4
	v_xor_b32_e32 v4, 2, v209
	v_cmp_lt_i32_e32 vcc, v4, v2
	s_load_dwordx2 s[0:1], s[2:3], 0x60
	s_nop 0
	s_load_dwordx2 s[2:3], s[2:3], 0xf0
	v_cndmask_b32_e32 v4, v209, v4, vcc
	v_lshlrev_b32_e32 v51, 2, v4
	v_xor_b32_e32 v4, 4, v209
	v_cmp_lt_i32_e32 vcc, v4, v2
	v_lshlrev_b32_e32 v48, 2, v18
	v_and_b32_e32 v3, 0xfc, v48
	v_cndmask_b32_e32 v4, v209, v4, vcc
	v_lshlrev_b32_e32 v52, 2, v4
	v_xor_b32_e32 v4, 8, v209
	v_cmp_lt_i32_e32 vcc, v4, v2
	s_movk_i32 s4, 0x400
	s_waitcnt lgkmcnt(0)
	s_add_u32 s0, s0, 0x1000
	v_cndmask_b32_e32 v4, v209, v4, vcc
	v_lshlrev_b32_e32 v53, 2, v4
	v_xor_b32_e32 v4, 16, v209
	v_cmp_lt_i32_e32 vcc, v4, v2
	v_lshl_add_u32 v49, v3, 2, 0
	v_cmp_gt_i32_e64 s[6:7], s4, v18
	v_cndmask_b32_e32 v4, v209, v4, vcc
	v_lshlrev_b32_e32 v54, 2, v4
	v_xor_b32_e32 v4, 32, v209
	v_cmp_lt_i32_e32 vcc, v4, v2
	s_addc_u32 s1, s1, 0
	s_mov_b64 s[4:5], 0xd580000
	v_cndmask_b32_e32 v2, v209, v4, vcc
	v_max_i32_e32 v4, 0x200, v18
	v_sub_u32_e32 v4, v4, v18
	v_add_u32_e32 v4, 0x1ff, v4
	v_lshrrev_b32_e32 v5, 9, v4
	v_add_u32_e32 v6, 1, v5
	v_add_u32_e32 v5, -1, v5
	v_lshlrev_b32_e32 v55, 2, v2
	v_lshlrev_b32_e32 v2, 1, v3
	v_mov_b32_e32 v3, 0
	v_lshrrev_b32_e32 v7, 1, v5
	v_lshl_add_u64 v[2:3], s[2:3], 0, v[2:3]
	s_movk_i32 s26, 0x1ff
	v_add_u32_e32 v7, 1, v7
	v_ashrrev_i32_e32 v1, 4, v18
	v_lshl_add_u64 v[20:21], v[2:3], 0, s[4:5]
	s_add_u32 s2, s2, 0x8000
	v_cmp_lt_u32_e64 s[8:9], s26, v4
	v_and_b32_e32 v4, 0xfffffe, v6
	v_and_b32_e32 v57, 3, v7
	s_mov_b64 s[4:5], 0x4280000
	v_and_b32_e32 v1, -4, v1
	s_addc_u32 s3, s3, 0
	v_lshl_add_u32 v56, v4, 9, v18
	v_add_u32_e32 v19, 0x200, v18
	v_cmp_lt_u32_e64 s[10:11], 5, v5
	v_and_b32_e32 v58, -4, v7
	v_cmp_ne_u32_e64 s[12:13], 0, v57
	v_cmp_ne_u32_e64 s[14:15], v6, v4
	s_waitcnt vmcnt(4)
	v_lshl_add_u64 v[22:23], v[2:3], 0, s[4:5]
	v_add_u32_e32 v59, 0, v48
	s_movk_i32 s27, 0x1000
	s_mov_b64 s[4:5], 0x800
	v_mov_b32_e32 v60, 0x358637bd
	s_mov_b32 s28, 0x800000
	s_mov_b32 s29, s83
	s_branch .LBB0_1192

.LBB0_1258:
	s_or_b64 exec, exec, s[8:9]
.LBB0_1259:
	s_or_b64 exec, exec, s[0:1]
	v_readlane_b32 s2, v254, 0
	v_readlane_b32 s3, v254, 1
	s_waitcnt lgkmcnt(0)
	s_barrier
	s_load_dwordx4 s[8:11], s[2:3], 0xe8
	s_mov_b64 s[0:1], 0xe80000
	v_lshl_add_u64 v[136:137], v[154:155], 0, s[0:1]
	v_mov_b32_e32 v139, 0
	v_mov_b32_e32 v131, v139
	s_waitcnt lgkmcnt(0)
	s_add_u32 s2, s10, 0xb280000
	s_addc_u32 s3, s11, 0
	s_add_u32 s0, s8, 0x7800000
	s_addc_u32 s1, s9, 0
	s_add_u32 s4, s8, 0x5800000
	s_mov_b64 s[6:7], 0xe80100
	v_lshl_add_u64 v[140:141], v[136:137], 0, v[130:131]
	s_addc_u32 s5, s9, 0
	v_lshl_add_u64 v[142:143], v[154:155], 0, s[6:7]
	s_mov_b32 s9, 0
	v_mov_b64_e32 v[144:145], 0x300
	v_mov_b64_e32 v[146:147], 0x2ff
	s_movk_i32 s28, 0x61
	s_mov_b64 s[12:13], 0x40000
	s_mov_b64 s[14:15], 0x80
	s_mov_b64 s[16:17], 0x40080
	s_mov_b64 s[18:19], 0x4280100
	s_movk_i32 s29, 0x108
	s_movk_i32 s30, 0x1080
	s_movk_i32 s31, 0x210
	s_mov_b32 s33, 0x7280000
	v_mov_b32_e32 v1, 1
	s_mov_b32 s34, 0
	s_waitcnt vmcnt(0)
	s_branch .LBB0_1262

.LBB0_1347:
	s_or_b64 exec, exec, s[8:9]
.LBB0_1348:
	s_or_b64 exec, exec, s[0:1]
	s_cmpk_gt_i32 s83, 0x3ff
	s_waitcnt lgkmcnt(0)
	s_barrier
	s_cbranch_scc1 .LBB0_1574
	v_readlane_b32 s0, v254, 0
	v_readlane_b32 s1, v254, 1
	s_load_dwordx2 s[0:1], s[0:1], 0xf0
	s_movk_i32 s2, 0x1d1
	v_cmp_gt_u32_e64 s[2:3], s2, v0
	s_mov_b32 s19, 0
	s_mov_b32 s24, s19
	s_waitcnt lgkmcnt(0)
	s_add_u32 s20, s0, 0x4280000
	s_addc_u32 s21, s1, 0
	s_add_u32 s11, s0, 0x7280000
	s_addc_u32 s12, s1, 0
	s_add_u32 s13, s0, 0x9280000
	v_writelane_b32 v254, s2, 15
	s_addc_u32 s14, s1, 0
	s_mov_b32 s25, s19
	v_writelane_b32 v254, s3, 16
	s_add_u32 s2, s0, 0xb280000
	v_writelane_b32 v254, s2, 17
	s_addc_u32 s2, s1, 0
	v_writelane_b32 v254, s2, 18
	s_add_u32 s2, s0, 0xc280000
	v_writelane_b32 v254, s2, 19
	s_addc_u32 s2, s1, 0
	v_writelane_b32 v254, s2, 20
	s_add_u32 s2, s0, 0x3880000
	v_writelane_b32 v254, s2, 21
	s_addc_u32 s2, s1, 0
	v_writelane_b32 v254, s2, 22
	s_add_u32 s0, s0, 0x3c80000
	v_writelane_b32 v254, s0, 23
	s_addc_u32 s0, s1, 0
	v_writelane_b32 v254, s0, 24
	v_writelane_b32 v254, s20, 25
	v_writelane_b32 v254, s21, 26
	v_writelane_b32 v254, s11, 27
	v_writelane_b32 v254, s12, 28
	v_writelane_b32 v254, s13, 29
	s_mov_b32 s26, s19
	s_mov_b32 s27, s19
	v_writelane_b32 v254, s14, 30
	v_writelane_b32 v254, s24, 31
	s_add_i32 s0, 0, 0x10000
	v_lshl_add_u32 v1, v0, 2, s0
	v_writelane_b32 v254, s25, 32
	v_mov_b32_e32 v137, 0
	s_movk_i32 s22, 0xa0
	s_mov_b32 s1, 0xf149f2ca
	s_mov_b32 s33, 0x3e38aa3b
	s_mov_b32 s0, 0x41800000
	s_mov_b32 s2, s83
	v_writelane_b32 v254, s26, 33
	v_writelane_b32 v254, s27, 34
	s_branch .LBB0_1352

.LBB0_1625:
	s_or_b64 exec, exec, s[8:9]
.LBB0_1626:
	s_or_b64 exec, exec, s[0:1]
	v_readlane_b32 s0, v254, 0
	v_readlane_b32 s1, v254, 1
	s_waitcnt lgkmcnt(0)
	s_barrier
	s_load_dwordx2 s[0:1], s[0:1], 0xf0
	s_mov_b64 s[2:3], 0x1480000
	v_mov_b32_e32 v139, 0
	v_lshl_add_u64 v[136:137], v[154:155], 0, s[2:3]
	v_mov_b32_e32 v131, v139
	s_waitcnt lgkmcnt(0)
	s_add_u32 s4, s0, 0xd580000
	v_lshl_add_u64 v[140:141], v[136:137], 0, v[130:131]
	s_addc_u32 s5, s1, 0
	s_mov_b32 s2, 0
	v_mov_b64_e32 v[142:143], 0x100
	v_mov_b64_e32 v[144:145], 0xff
	s_mov_b64 s[8:9], 0x40000
	s_mov_b64 s[10:11], 0x80
	s_mov_b32 s3, 0xa000
	s_mov_b64 s[12:13], 0x40080
	s_movk_i32 s22, 0x108
	s_mov_b64 s[14:15], 0xa000
	s_movk_i32 s23, 0x210
	v_mov_b32_e32 v1, 1
	s_branch .LBB0_1628

.LBB0_1705:
	s_or_b64 exec, exec, s[8:9]
.LBB0_1706:
	s_or_b64 exec, exec, s[0:1]
	v_readlane_b32 s0, v254, 13
	v_readlane_b32 s1, v254, 14
	v_mov_b32_e32 v18, v0
	s_and_b64 vcc, exec, s[0:1]
	s_waitcnt lgkmcnt(0)
	s_barrier
	s_cbranch_vccnz .LBB0_1724
	v_and_b32_e32 v2, 64, v209
	v_add_u32_e32 v2, 64, v2
	v_xor_b32_e32 v4, 1, v209
	v_cmp_lt_i32_e32 vcc, v4, v2
	v_readlane_b32 s2, v254, 0
	v_readlane_b32 s3, v254, 1
	v_cndmask_b32_e32 v4, v209, v4, vcc
	v_lshlrev_b32_e32 v50, 2, v4
	v_xor_b32_e32 v4, 2, v209
	v_cmp_lt_i32_e32 vcc, v4, v2
	s_load_dwordx2 s[0:1], s[2:3], 0x68
	s_load_dwordx2 s[14:15], s[2:3], 0xf0
	v_cndmask_b32_e32 v4, v209, v4, vcc
	v_lshlrev_b32_e32 v51, 2, v4
	v_xor_b32_e32 v4, 4, v209
	v_cmp_lt_i32_e32 vcc, v4, v2
	v_lshlrev_b32_e32 v48, 2, v18
	v_and_b32_e32 v3, 0xfc, v48
	v_cndmask_b32_e32 v4, v209, v4, vcc
	v_lshlrev_b32_e32 v52, 2, v4
	v_xor_b32_e32 v4, 8, v209
	v_cmp_lt_i32_e32 vcc, v4, v2
	s_movk_i32 s2, 0x400
	s_waitcnt lgkmcnt(0)
	s_add_u32 s0, s0, 0x1000
	v_cndmask_b32_e32 v4, v209, v4, vcc
	v_lshlrev_b32_e32 v53, 2, v4
	v_xor_b32_e32 v4, 16, v209
	v_cmp_lt_i32_e32 vcc, v4, v2
	v_lshl_add_u32 v49, v3, 2, 0
	v_cmp_gt_i32_e64 s[4:5], s2, v18
	v_cndmask_b32_e32 v4, v209, v4, vcc
	v_lshlrev_b32_e32 v54, 2, v4
	v_xor_b32_e32 v4, 32, v209
	v_cmp_lt_i32_e32 vcc, v4, v2
	s_addc_u32 s1, s1, 0
	s_mov_b64 s[2:3], 0xd580000
	v_cndmask_b32_e32 v2, v209, v4, vcc
	v_max_i32_e32 v4, 0x200, v18
	v_sub_u32_e32 v4, v4, v18
	v_add_u32_e32 v4, 0x1ff, v4
	v_lshlrev_b32_e32 v55, 2, v2
	v_lshlrev_b32_e32 v2, 1, v3
	v_mov_b32_e32 v3, 0
	v_lshrrev_b32_e32 v5, 9, v4
	v_lshl_add_u64 v[2:3], s[14:15], 0, v[2:3]
	v_add_u32_e32 v6, 1, v5
	v_add_u32_e32 v5, -1, v5
	v_lshl_add_u64 v[20:21], v[2:3], 0, s[2:3]
	s_add_u32 s2, s14, 0x8000
	v_lshrrev_b32_e32 v7, 1, v5
	s_addc_u32 s3, s15, 0
	s_movk_i32 s28, 0x1ff
	v_add_u32_e32 v7, 1, v7
	v_ashrrev_i32_e32 v1, 4, v18
	v_cmp_lt_u32_e64 s[6:7], s28, v4
	v_and_b32_e32 v4, 0xfffffe, v6
	v_and_b32_e32 v57, 3, v7
	s_mov_b64 s[16:17], 0x4280000
	s_add_u32 s29, s14, 0xb000
	v_and_b32_e32 v1, -4, v1
	v_lshl_add_u32 v56, v4, 9, v18
	v_add_u32_e32 v19, 0x200, v18
	v_cmp_lt_u32_e64 s[8:9], 5, v5
	v_and_b32_e32 v58, -4, v7
	v_cmp_ne_u32_e64 s[10:11], 0, v57
	v_cmp_ne_u32_e64 s[12:13], v6, v4
	v_lshl_add_u64 v[22:23], v[2:3], 0, s[16:17]
	v_add_u32_e32 v59, 0, v48
	s_addc_u32 s30, s15, 0
	s_movk_i32 s31, 0x3000
	s_movk_i32 s33, 0x4000
	s_mov_b64 s[16:17], 0x800
	v_mov_b32_e32 v60, 0x358637bd
	s_mov_b32 s34, 0x800000
	s_mov_b32 s35, s83
	s_branch .LBB0_1709

.LBB0_1775:
	s_or_b64 exec, exec, s[8:9]
.LBB0_1776:
	s_or_b64 exec, exec, s[0:1]
	v_readlane_b32 s4, v254, 0
	s_mov_b64 s[0:1], 0x2180000
	v_readlane_b32 s5, v254, 1
	s_waitcnt lgkmcnt(0)
	s_barrier
	v_lshl_add_u64 v[136:137], v[154:155], 0, s[0:1]
	s_load_dwordx4 s[0:3], s[4:5], 0xd0
	v_mov_b32_e32 v139, 0
	s_load_dwordx2 s[4:5], s[4:5], 0xf0
	v_mov_b32_e32 v131, v139
	v_lshl_add_u64 v[140:141], v[136:137], 0, v[130:131]
	s_waitcnt lgkmcnt(0)
	s_add_u32 s0, s0, 0x10800
	s_addc_u32 s1, s1, 0
	s_add_u32 s10, s2, 0x5800
	s_addc_u32 s11, s3, 0
	s_add_u32 s12, s4, 0x7280000
	s_addc_u32 s13, s5, 0
	s_add_u32 s2, s4, 0xca80000
	s_addc_u32 s3, s5, 0
	s_mov_b64 s[4:5], 0x2180100
	s_mov_b64 s[8:9], 0x5800
	v_lshl_add_u64 v[142:143], v[154:155], 0, s[4:5]
	s_mov_b32 s14, 0
	v_mov_b64_e32 v[144:145], 0x580
	v_mov_b64_e32 v[146:147], 0x57f
	s_movk_i32 s33, 0xb1
	s_movk_i32 s44, 0x2000
	s_movk_i32 s45, 0x400
	s_mov_b64 s[16:17], 0x40000
	s_mov_b64 s[18:19], 0x80
	s_mov_b64 s[20:21], 0x40080
	s_mov_b64 s[22:23], 0x4280100
	s_movk_i32 s46, 0xff
	s_movk_i32 s47, 0x108
	s_movk_i32 s48, 0x5000
	s_mov_b64 s[24:25], 0xb000
	s_mov_b64 s[26:27], 0x2c00
	s_mov_b64 s[28:29], 0x8400
	s_mov_b64 s[30:31], 0xdc00
	s_movk_i32 s49, 0xfdf0
	s_movk_i32 s50, 0x1600
	s_movk_i32 s51, 0x210
	s_movk_i32 s52, 0x1ff
	s_movk_i32 s53, 0x5800
	v_mov_b32_e32 v131, 1
	s_mov_b32 s54, 0
	s_branch .LBB0_1779

.LBB0_1881:
	s_or_b64 exec, exec, s[8:9]
.LBB0_1882:
	s_or_b64 exec, exec, s[0:1]
	v_readlane_b32 s0, v254, 0
	v_readlane_b32 s1, v254, 1
	s_waitcnt lgkmcnt(0)
	s_barrier
	s_load_dwordx4 s[8:11], s[0:1], 0xd0
	s_nop 0
	s_load_dwordx2 s[0:1], s[0:1], 0xf0
	s_mov_b64 s[2:3], 0x3200000
	v_lshl_add_u64 v[136:137], v[154:155], 0, s[2:3]
	v_mov_b32_e32 v131, 0
	v_lshl_add_u64 v[138:139], v[136:137], 0, v[130:131]
	s_waitcnt lgkmcnt(0)
	s_add_u32 s2, s0, 0xca80000
	s_addc_u32 s3, s1, 0
	s_add_u32 s6, s0, 0xd580000
	s_addc_u32 s7, s1, 0
	s_add_u32 s12, s0, 0x7280000
	s_addc_u32 s13, s1, 0
	s_mov_b32 s33, 0
	v_mov_b64_e32 v[140:141], 0x100
	v_mov_b64_e32 v[142:143], 0xff
	s_movk_i32 s46, 0xb00
	s_movk_i32 s47, 0x1600
	s_movk_i32 s48, 0xff80
	s_movk_i32 s49, 0x7fff
	s_mov_b64 s[14:15], 0x400
	s_movk_i32 s50, 0x8ff
	s_mov_b64 s[16:17], 0xb0000
	s_mov_b64 s[18:19], 0x80
	s_mov_b64 s[20:21], 0xb0080
	s_mov_b32 s51, 0xb000
	s_movk_i32 s52, 0x108
	s_mov_b64 s[22:23], 0xd000
	s_mov_b32 s53, 0xd000
	s_movk_i32 s54, 0x210
	v_mov_b32_e32 v1, 0x1600
	v_mov_b32_e32 v158, 1
	v_mov_b32_e32 v159, 0x160000
	s_branch .LBB0_1884

.LBB0_1972:
	s_or_b64 exec, exec, s[2:3]
	s_mov_b64 s[2:3], exec
	v_mbcnt_lo_u32_b32 v1, s2, 0
	v_mbcnt_hi_u32_b32 v1, s3, v1
	v_cmp_eq_u32_e32 vcc, 0, v1
	s_and_saveexec_b64 s[6:7], vcc
	s_cbranch_execz .LBB0_1974
	s_bcnt1_i32_b64 s2, s[2:3]
	v_mov_b32_e32 v1, 0x2000
	v_mov_b32_e32 v2, s2
.LBB0_1974:
	s_or_b64 exec, exec, s[6:7]
.LBB0_1975:
	s_or_b64 exec, exec, s[0:1]
	s_waitcnt lgkmcnt(0)
	s_barrier
	v_readlane_b32 s0, v254, 0
	v_readlane_b32 s1, v254, 1
	v_lshrrev_b32_e32 v2, 6, v0
	v_and_b32_e32 v1, 63, v0
	s_load_dwordx4 s[4:7], s[0:1], 0xe8
	s_load_dwordx2 s[8:9], s[0:1], 0x70
	v_readfirstlane_b32 s10, v2
	s_lshl_b32 s11, s83, 3
	s_add_i32 s11, s11, s10
	s_lshl_b32 s12, s84, 3
	s_add_i32 s13, s11, s12
	s_cmp_gt_i32 s11, 0x3fff
	s_cbranch_scc1 .Lfn_end
	v_lshlrev_b32_e32 v3, 3, v1
	v_lshlrev_b32_e32 v4, 4, v1
	v_xor_b32_e32 v5, 1, v1
	v_lshlrev_b32_e32 v8, 2, v5
	v_xor_b32_e32 v5, 2, v1
	v_lshlrev_b32_e32 v9, 2, v5
	v_xor_b32_e32 v5, 4, v1
	v_lshlrev_b32_e32 v10, 2, v5
	v_xor_b32_e32 v5, 8, v1
	v_lshlrev_b32_e32 v11, 2, v5
	v_xor_b32_e32 v5, 16, v1
	v_lshlrev_b32_e32 v12, 2, v5
	v_xor_b32_e32 v5, 32, v1
	v_lshlrev_b32_e32 v13, 2, v5
	v_mov_b32_e32 v14, 0x358637bd
	s_mov_b32 s22, 0x800000
	s_waitcnt lgkmcnt(0)
	s_add_u32 s6, s6, 0xd580000
	s_addc_u32 s7, s7, 0
	global_load_dwordx4 v[60:63], v4, s[8:9]
	global_load_dwordx4 v[64:67], v4, s[8:9] offset:1024
	global_load_dwordx4 v[68:71], v4, s[8:9] offset:2048
	global_load_dwordx4 v[72:75], v4, s[8:9] offset:3072
	s_min_i32 s14, s11, 0x3fff
	s_lshl_b32 s16, s14, 11
	s_add_u32 s16, s6, s16
	s_addc_u32 s17, s7, 0
	global_load_dwordx2 v[80:81], v3, s[16:17]
	global_load_dwordx2 v[82:83], v3, s[16:17] offset:512
	global_load_dwordx2 v[84:85], v3, s[16:17] offset:1024
	global_load_dwordx2 v[86:87], v3, s[16:17] offset:1536
	s_min_i32 s14, s13, 0x3fff
	s_lshl_b32 s18, s14, 11
	s_add_u32 s18, s6, s18
	s_addc_u32 s19, s7, 0
	global_load_dwordx2 v[88:89], v3, s[18:19]
	global_load_dwordx2 v[90:91], v3, s[18:19] offset:512
	global_load_dwordx2 v[92:93], v3, s[18:19] offset:1024
	global_load_dwordx2 v[94:95], v3, s[18:19] offset:1536
	s_waitcnt vmcnt(4)
